# UP GEMM K-loop: LDS-DMA addresses in saddr form (SGPR base + 32-bit VGPR offset) instead of 16 v_lshl_add_u64 per iteration
# speedup vs baseline: 1.0215x; 1.0029x over previous
.LBB0_565:
	s_add_u32 s40, s38, 0xfffc0080
	s_addc_u32 s41, s39, -1
	s_add_i32 s52, 0, 0x10000
	s_cmp_eq_u32 s51, 12
	s_cselect_b32 s43, s21, s41
	s_cselect_b32 s42, s47, s40
	v_add_u32_e32 v0, s52, v141
	s_cselect_b32 s41, s19, s50
	s_cselect_b32 s40, s48, s49
	s_add_i32 s54, 0, 0x14000
	ds_read_b128 v[146:149], v0
	ds_read_b128 v[150:153], v0 offset:1024
	ds_read_b128 v[154:157], v0 offset:2048
	ds_read_b128 v[158:161], v0 offset:3072
	v_add_u32_e32 v0, s54, v141
	ds_read_b128 v[162:165], v0
	ds_read_b128 v[166:169], v0 offset:1024
	ds_read_b128 v[170:173], v0 offset:2048
	ds_read_b128 v[174:177], v0 offset:3072
	s_add_i32 m0, s8, 0xc000
	ds_read_b128 v[178:181], v145
	ds_read_b128 v[182:185], v145 offset:1024
	ds_read_b128 v[186:189], v145 offset:2048
	ds_read_b128 v[190:193], v145 offset:3072
	ds_read_b128 v[194:197], v145 offset:4096
	ds_read_b128 v[208:211], v145 offset:5120
	ds_read_b128 v[212:215], v145 offset:6144
	ds_read_b128 v[216:219], v145 offset:7168
	global_load_lds_dwordx4 v138, s[38:39]
	s_add_i32 m0, s8, 0xe000
	s_nop 0
	global_load_lds_dwordx4 v136, s[38:39]
	s_waitcnt vmcnt(8)
	s_waitcnt lgkmcnt(0)
	s_barrier
	s_setprio 1
	s_waitcnt lgkmcnt(0)
	v_mfma_f32_16x16x32_bf16 v[130:133], v[146:149], v[178:181], v[130:133]
	v_mfma_f32_16x16x32_bf16 v[126:129], v[154:157], v[178:181], v[126:129]
	v_mfma_f32_16x16x32_bf16 v[114:117], v[146:149], v[186:189], v[114:117]
	v_mfma_f32_16x16x32_bf16 v[110:113], v[154:157], v[186:189], v[110:113]
	v_mfma_f32_16x16x32_bf16 v[98:101], v[146:149], v[194:197], v[98:101]
	v_mfma_f32_16x16x32_bf16 v[90:93], v[154:157], v[194:197], v[90:93]
	v_mfma_f32_16x16x32_bf16 v[78:81], v[146:149], v[212:215], v[78:81]
	v_mfma_f32_16x16x32_bf16 v[74:77], v[154:157], v[212:215], v[74:77]
	v_mfma_f32_16x16x32_bf16 v[130:133], v[150:153], v[182:185], v[130:133]
	v_mfma_f32_16x16x32_bf16 v[126:129], v[158:161], v[182:185], v[126:129]
	v_mfma_f32_16x16x32_bf16 v[114:117], v[150:153], v[190:193], v[114:117]
	v_mfma_f32_16x16x32_bf16 v[110:113], v[158:161], v[190:193], v[110:113]
	v_mfma_f32_16x16x32_bf16 v[98:101], v[150:153], v[208:211], v[98:101]
	v_mfma_f32_16x16x32_bf16 v[90:93], v[158:161], v[208:211], v[90:93]
	v_mfma_f32_16x16x32_bf16 v[78:81], v[150:153], v[216:219], v[78:81]
	v_mfma_f32_16x16x32_bf16 v[74:77], v[158:161], v[216:219], v[74:77]
	s_setprio 0
	s_setprio 1
	v_mfma_f32_16x16x32_bf16 v[122:125], v[162:165], v[178:181], v[122:125]
	v_mfma_f32_16x16x32_bf16 v[118:121], v[170:173], v[178:181], v[118:121]
	v_mfma_f32_16x16x32_bf16 v[106:109], v[162:165], v[186:189], v[106:109]
	v_mfma_f32_16x16x32_bf16 v[102:105], v[170:173], v[186:189], v[102:105]
	v_mfma_f32_16x16x32_bf16 v[86:89], v[162:165], v[194:197], v[86:89]
	v_mfma_f32_16x16x32_bf16 v[82:85], v[170:173], v[194:197], v[82:85]
	v_mfma_f32_16x16x32_bf16 v[70:73], v[162:165], v[212:215], v[70:73]
	v_mfma_f32_16x16x32_bf16 v[66:69], v[170:173], v[212:215], v[66:69]
	v_mfma_f32_16x16x32_bf16 v[122:125], v[166:169], v[182:185], v[122:125]
	v_mfma_f32_16x16x32_bf16 v[118:121], v[174:177], v[182:185], v[118:121]
	v_mfma_f32_16x16x32_bf16 v[106:109], v[166:169], v[190:193], v[106:109]
	v_mfma_f32_16x16x32_bf16 v[102:105], v[174:177], v[190:193], v[102:105]
	v_mfma_f32_16x16x32_bf16 v[86:89], v[166:169], v[208:211], v[86:89]
	v_mfma_f32_16x16x32_bf16 v[82:85], v[174:177], v[208:211], v[82:85]
	v_mfma_f32_16x16x32_bf16 v[70:73], v[166:169], v[216:219], v[70:73]
	v_mfma_f32_16x16x32_bf16 v[66:69], v[174:177], v[216:219], v[66:69]
	s_setprio 0
	s_barrier
	s_add_i32 s52, s52, s6
	s_mov_b32 m0, s52
	ds_read_b128 v[178:181], v145 offset:16384
	ds_read_b128 v[182:185], v145 offset:17408
	ds_read_b128 v[186:189], v145 offset:18432
	ds_read_b128 v[190:193], v145 offset:19456
	ds_read_b128 v[194:197], v145 offset:20480
	ds_read_b128 v[208:211], v145 offset:21504
	ds_read_b128 v[212:215], v145 offset:22528
	ds_read_b128 v[216:219], v145 offset:23552
	global_load_lds_dwordx4 v134, s[40:41]
	s_add_i32 m0, s52, 0x2000
	s_add_u32 s52, s40, 0x40000
	s_addc_u32 s53, s41, 0
	s_add_i32 s54, s54, s6
	global_load_lds_dwordx4 v94, s[40:41]
	s_mov_b32 m0, s54
	s_nop 0
	global_load_lds_dwordx4 v134, s[52:53]
	s_add_i32 m0, s54, 0x2000
	s_nop 0
	global_load_lds_dwordx4 v94, s[52:53]
	s_mov_b32 m0, s8
	s_nop 0
	global_load_lds_dwordx4 v134, s[42:43]
	s_mov_b32 m0, s9
	s_nop 0
	global_load_lds_dwordx4 v94, s[42:43]
	s_waitcnt vmcnt(8)
	s_waitcnt lgkmcnt(0)
	s_barrier
	s_setprio 1
	s_waitcnt lgkmcnt(0)
	v_mfma_f32_16x16x32_bf16 v[62:65], v[146:149], v[178:181], v[62:65]
	v_mfma_f32_16x16x32_bf16 v[58:61], v[154:157], v[178:181], v[58:61]
	v_mfma_f32_16x16x32_bf16 v[46:49], v[146:149], v[186:189], v[46:49]
	v_mfma_f32_16x16x32_bf16 v[42:45], v[154:157], v[186:189], v[42:45]
	v_mfma_f32_16x16x32_bf16 v[30:33], v[146:149], v[194:197], v[30:33]
	v_mfma_f32_16x16x32_bf16 v[26:29], v[154:157], v[194:197], v[26:29]
	v_mfma_f32_16x16x32_bf16 v[14:17], v[146:149], v[212:215], v[14:17]
	v_mfma_f32_16x16x32_bf16 v[10:13], v[154:157], v[212:215], v[10:13]
	v_mfma_f32_16x16x32_bf16 v[62:65], v[150:153], v[182:185], v[62:65]
	v_mfma_f32_16x16x32_bf16 v[58:61], v[158:161], v[182:185], v[58:61]
	v_mfma_f32_16x16x32_bf16 v[46:49], v[150:153], v[190:193], v[46:49]
	v_mfma_f32_16x16x32_bf16 v[42:45], v[158:161], v[190:193], v[42:45]
	v_mfma_f32_16x16x32_bf16 v[30:33], v[150:153], v[208:211], v[30:33]
	v_mfma_f32_16x16x32_bf16 v[26:29], v[158:161], v[208:211], v[26:29]
	v_mfma_f32_16x16x32_bf16 v[14:17], v[150:153], v[216:219], v[14:17]
	v_mfma_f32_16x16x32_bf16 v[10:13], v[158:161], v[216:219], v[10:13]
	s_setprio 0
	s_setprio 1
	v_mfma_f32_16x16x32_bf16 v[54:57], v[162:165], v[178:181], v[54:57]
	v_mfma_f32_16x16x32_bf16 v[50:53], v[170:173], v[178:181], v[50:53]
	v_mfma_f32_16x16x32_bf16 v[38:41], v[162:165], v[186:189], v[38:41]
	v_mfma_f32_16x16x32_bf16 v[34:37], v[170:173], v[186:189], v[34:37]
	v_mfma_f32_16x16x32_bf16 v[22:25], v[162:165], v[194:197], v[22:25]
	v_mfma_f32_16x16x32_bf16 v[18:21], v[170:173], v[194:197], v[18:21]
	v_mfma_f32_16x16x32_bf16 v[6:9], v[162:165], v[212:215], v[6:9]
	v_mfma_f32_16x16x32_bf16 v[2:5], v[170:173], v[212:215], v[2:5]
	v_mfma_f32_16x16x32_bf16 v[54:57], v[166:169], v[182:185], v[54:57]
	v_mfma_f32_16x16x32_bf16 v[50:53], v[174:177], v[182:185], v[50:53]
	v_mfma_f32_16x16x32_bf16 v[38:41], v[166:169], v[190:193], v[38:41]
	v_mfma_f32_16x16x32_bf16 v[34:37], v[174:177], v[190:193], v[34:37]
	v_mfma_f32_16x16x32_bf16 v[22:25], v[166:169], v[208:211], v[22:25]
	v_mfma_f32_16x16x32_bf16 v[18:21], v[174:177], v[208:211], v[18:21]
	v_mfma_f32_16x16x32_bf16 v[6:9], v[166:169], v[216:219], v[6:9]
	v_mfma_f32_16x16x32_bf16 v[2:5], v[174:177], v[216:219], v[2:5]
	s_setprio 0
	s_barrier
	s_add_i32 s52, 0, 0x18000
	v_add_u32_e32 v0, s52, v141
	s_add_i32 s53, 0, 0x1c000
	ds_read_b128 v[146:149], v0
	ds_read_b128 v[150:153], v0 offset:1024
	ds_read_b128 v[154:157], v0 offset:2048
	ds_read_b128 v[158:161], v0 offset:3072
	v_add_u32_e32 v0, s53, v141
	ds_read_b128 v[162:165], v0
	ds_read_b128 v[166:169], v0 offset:1024
	ds_read_b128 v[170:173], v0 offset:2048
	ds_read_b128 v[174:177], v0 offset:3072
	s_add_u32 s42, s42, 0x40000
	s_addc_u32 s43, s43, 0
	s_mov_b32 m0, s12
	ds_read_b128 v[178:181], v145 offset:32768
	ds_read_b128 v[182:185], v145 offset:33792
	ds_read_b128 v[186:189], v145 offset:34816
	ds_read_b128 v[190:193], v145 offset:35840
	ds_read_b128 v[194:197], v145 offset:36864
	ds_read_b128 v[208:211], v145 offset:37888
	ds_read_b128 v[212:215], v145 offset:38912
	ds_read_b128 v[216:219], v145 offset:39936
	global_load_lds_dwordx4 v134, s[42:43]
	s_mov_b32 m0, s13
	s_nop 0
	global_load_lds_dwordx4 v94, s[42:43]
	s_waitcnt vmcnt(8)
	s_waitcnt lgkmcnt(0)
	s_barrier
	s_setprio 1
	s_waitcnt lgkmcnt(0)
	v_mfma_f32_16x16x32_bf16 v[130:133], v[146:149], v[178:181], v[130:133]
	v_mfma_f32_16x16x32_bf16 v[126:129], v[154:157], v[178:181], v[126:129]
	v_mfma_f32_16x16x32_bf16 v[114:117], v[146:149], v[186:189], v[114:117]
	v_mfma_f32_16x16x32_bf16 v[110:113], v[154:157], v[186:189], v[110:113]
	v_mfma_f32_16x16x32_bf16 v[98:101], v[146:149], v[194:197], v[98:101]
	v_mfma_f32_16x16x32_bf16 v[90:93], v[154:157], v[194:197], v[90:93]
	v_mfma_f32_16x16x32_bf16 v[78:81], v[146:149], v[212:215], v[78:81]
	v_mfma_f32_16x16x32_bf16 v[74:77], v[154:157], v[212:215], v[74:77]
	v_mfma_f32_16x16x32_bf16 v[130:133], v[150:153], v[182:185], v[130:133]
	v_mfma_f32_16x16x32_bf16 v[126:129], v[158:161], v[182:185], v[126:129]
	v_mfma_f32_16x16x32_bf16 v[114:117], v[150:153], v[190:193], v[114:117]
	v_mfma_f32_16x16x32_bf16 v[110:113], v[158:161], v[190:193], v[110:113]
	v_mfma_f32_16x16x32_bf16 v[98:101], v[150:153], v[208:211], v[98:101]
	v_mfma_f32_16x16x32_bf16 v[90:93], v[158:161], v[208:211], v[90:93]
	v_mfma_f32_16x16x32_bf16 v[78:81], v[150:153], v[216:219], v[78:81]
	v_mfma_f32_16x16x32_bf16 v[74:77], v[158:161], v[216:219], v[74:77]
	s_setprio 0
	s_setprio 1
	v_mfma_f32_16x16x32_bf16 v[122:125], v[162:165], v[178:181], v[122:125]
	v_mfma_f32_16x16x32_bf16 v[118:121], v[170:173], v[178:181], v[118:121]
	v_mfma_f32_16x16x32_bf16 v[106:109], v[162:165], v[186:189], v[106:109]
	v_mfma_f32_16x16x32_bf16 v[102:105], v[170:173], v[186:189], v[102:105]
	v_mfma_f32_16x16x32_bf16 v[86:89], v[162:165], v[194:197], v[86:89]
	v_mfma_f32_16x16x32_bf16 v[82:85], v[170:173], v[194:197], v[82:85]
	v_mfma_f32_16x16x32_bf16 v[70:73], v[162:165], v[212:215], v[70:73]
	v_mfma_f32_16x16x32_bf16 v[66:69], v[170:173], v[212:215], v[66:69]
	v_mfma_f32_16x16x32_bf16 v[122:125], v[166:169], v[182:185], v[122:125]
	v_mfma_f32_16x16x32_bf16 v[118:121], v[174:177], v[182:185], v[118:121]
	v_mfma_f32_16x16x32_bf16 v[106:109], v[166:169], v[190:193], v[106:109]
	v_mfma_f32_16x16x32_bf16 v[102:105], v[174:177], v[190:193], v[102:105]
	v_mfma_f32_16x16x32_bf16 v[86:89], v[166:169], v[208:211], v[86:89]
	v_mfma_f32_16x16x32_bf16 v[82:85], v[174:177], v[208:211], v[82:85]
	v_mfma_f32_16x16x32_bf16 v[70:73], v[166:169], v[216:219], v[70:73]
	v_mfma_f32_16x16x32_bf16 v[66:69], v[174:177], v[216:219], v[66:69]
	s_setprio 0
	s_barrier
	s_add_i32 s54, s52, s6
	s_add_i32 m0, s54, 0xffffff80
	ds_read_b128 v[178:181], v145 offset:49152
	ds_read_b128 v[182:185], v145 offset:50176
	ds_read_b128 v[186:189], v145 offset:51200
	ds_read_b128 v[190:193], v145 offset:52224
	ds_read_b128 v[194:197], v145 offset:53248
	ds_read_b128 v[208:211], v145 offset:54272
	ds_read_b128 v[212:215], v145 offset:55296
	ds_read_b128 v[216:219], v145 offset:56320
	global_load_lds_dwordx4 v134, s[40:41] offset:128
	s_add_i32 m0, s54, 0x1f80
	s_nop 0
	global_load_lds_dwordx4 v94, s[40:41] offset:128
	s_add_i32 s54, s53, s6
	s_add_u32 s40, s40, 0x40080
	s_addc_u32 s41, s41, 0
	s_mov_b32 m0, s54
	s_nop 0
	global_load_lds_dwordx4 v134, s[40:41]
	s_add_i32 m0, s54, 0x2000
	s_nop 0
	global_load_lds_dwordx4 v94, s[40:41]
	s_add_u32 s42, s42, 0xfffc0080
	s_addc_u32 s43, s43, -1
	s_mov_b32 m0, s28
	s_nop 0
	global_load_lds_dwordx4 v134, s[42:43]
	s_mov_b32 m0, s29
	s_nop 0
	global_load_lds_dwordx4 v94, s[42:43]
	s_waitcnt vmcnt(8)
	s_waitcnt lgkmcnt(0)
	s_barrier
	s_setprio 1
	s_waitcnt lgkmcnt(0)
	v_mfma_f32_16x16x32_bf16 v[62:65], v[146:149], v[178:181], v[62:65]
	v_mfma_f32_16x16x32_bf16 v[58:61], v[154:157], v[178:181], v[58:61]
	v_mfma_f32_16x16x32_bf16 v[46:49], v[146:149], v[186:189], v[46:49]
	v_mfma_f32_16x16x32_bf16 v[42:45], v[154:157], v[186:189], v[42:45]
	v_mfma_f32_16x16x32_bf16 v[30:33], v[146:149], v[194:197], v[30:33]
	v_mfma_f32_16x16x32_bf16 v[26:29], v[154:157], v[194:197], v[26:29]
	v_mfma_f32_16x16x32_bf16 v[14:17], v[146:149], v[212:215], v[14:17]
	v_mfma_f32_16x16x32_bf16 v[10:13], v[154:157], v[212:215], v[10:13]
	v_mfma_f32_16x16x32_bf16 v[62:65], v[150:153], v[182:185], v[62:65]
	v_mfma_f32_16x16x32_bf16 v[58:61], v[158:161], v[182:185], v[58:61]
	v_mfma_f32_16x16x32_bf16 v[46:49], v[150:153], v[190:193], v[46:49]
	v_mfma_f32_16x16x32_bf16 v[42:45], v[158:161], v[190:193], v[42:45]
	v_mfma_f32_16x16x32_bf16 v[30:33], v[150:153], v[208:211], v[30:33]
	v_mfma_f32_16x16x32_bf16 v[26:29], v[158:161], v[208:211], v[26:29]
	v_mfma_f32_16x16x32_bf16 v[14:17], v[150:153], v[216:219], v[14:17]
	v_mfma_f32_16x16x32_bf16 v[10:13], v[158:161], v[216:219], v[10:13]
	s_setprio 0
	s_setprio 1
	v_mfma_f32_16x16x32_bf16 v[54:57], v[162:165], v[178:181], v[54:57]
	v_mfma_f32_16x16x32_bf16 v[50:53], v[170:173], v[178:181], v[50:53]
	v_mfma_f32_16x16x32_bf16 v[38:41], v[162:165], v[186:189], v[38:41]
	v_mfma_f32_16x16x32_bf16 v[34:37], v[170:173], v[186:189], v[34:37]
	v_mfma_f32_16x16x32_bf16 v[22:25], v[162:165], v[194:197], v[22:25]
	v_mfma_f32_16x16x32_bf16 v[18:21], v[170:173], v[194:197], v[18:21]
	v_mfma_f32_16x16x32_bf16 v[6:9], v[162:165], v[212:215], v[6:9]
	v_mfma_f32_16x16x32_bf16 v[2:5], v[170:173], v[212:215], v[2:5]
	v_mfma_f32_16x16x32_bf16 v[54:57], v[166:169], v[182:185], v[54:57]
	v_mfma_f32_16x16x32_bf16 v[50:53], v[174:177], v[182:185], v[50:53]
	v_mfma_f32_16x16x32_bf16 v[38:41], v[166:169], v[190:193], v[38:41]
	v_mfma_f32_16x16x32_bf16 v[34:37], v[174:177], v[190:193], v[34:37]
	v_mfma_f32_16x16x32_bf16 v[22:25], v[166:169], v[208:211], v[22:25]
	v_mfma_f32_16x16x32_bf16 v[18:21], v[174:177], v[208:211], v[18:21]
	v_mfma_f32_16x16x32_bf16 v[6:9], v[166:169], v[216:219], v[6:9]
	v_mfma_f32_16x16x32_bf16 v[2:5], v[174:177], v[216:219], v[2:5]
	s_setprio 0
	s_barrier
	s_add_i32 s51, s51, 2
	s_add_u32 s49, s49, 0x100
	s_addc_u32 s50, s50, 0
	s_add_u32 s38, s38, 0x100
	s_addc_u32 s39, s39, 0
	s_cmp_gt_u32 s51, 13
	s_cbranch_scc0 .LBB0_565
	s_and_b64 vcc, exec, s[10:11]
	s_cbranch_vccz .LBB0_568
	s_barrier
